# S5 item BT3 stage re-dealt: Toeplitz pieces in rounds 0-3, C.lambda pieces in rounds 4-5 (each wave runs one code path per round)
# speedup vs baseline: 1.0046x; 1.0046x over previous
.Lssa_493:
	v_add_u32_e32 v4, s91, v208
	s_cmpk_lt_u32 s91, 0x800
	s_cbranch_scc0 .Lbt3_modeB
	v_lshrrev_b32_e32 v5, 5, v4
	v_and_b32_e32 v51, 31, v4
	s_branch .Lbt3_idx
.Lbt3_modeB:
	v_add_u32_e32 v4, 0xfffff800, v4
	v_lshrrev_b32_e32 v5, 4, v4
	v_and_b32_e32 v51, 15, v4
	v_or_b32_e32 v51, 32, v51
.Lbt3_idx:
	v_lshlrev_b32_e32 v6, 5, v5
	v_add_u32_e32 v5, s86, v5
	v_lshlrev_b32_e32 v4, 3, v51
	v_lshrrev_b32_e32 v52, 4, v5
	v_bfe_u32 v53, v6, 5, 4
	v_and_b32_e32 v13, 7, v53
	v_lshlrev_b32_e32 v13, 4, v13
	v_cmp_lt_u32_e32 vcc, 31, v51
	s_and_saveexec_b64 s[4:5], vcc
	s_xor_b64 s[4:5], exec, s[4:5]
	s_cbranch_execz .Lssa_495
	v_and_b32_e32 v44, 56, v4
	v_lshl_add_u32 v62, v53, 9, 0
	v_lshl_add_u32 v63, v52, 6, 64
	v_lshl_add_u32 v6, v44, 3, v62
	v_xor_b32_e32 v6, v13, v6
	ds_read_b128 v[52:55], v6 offset:16896
	v_or_b32_e32 v6, v63, v44
	v_lshl_add_u32 v6, v6, 3, 0
	ds_read_b128 v[56:59], v6
	v_and_b32_e32 v8, 56, v51
	s_waitcnt lgkmcnt(1)
	v_mov_b32_e32 v6, v53
	v_mov_b32_e32 v7, v54
	v_cmp_eq_u32_e32 vcc, 32, v8
	s_waitcnt lgkmcnt(0)
	v_mov_b32_e32 v50, v56
	v_mov_b32_e32 v51, v59
	v_mov_b32_e32 v48, v57
	v_mov_b32_e32 v49, v58
	v_pk_mul_f32 v[6:7], v[6:7], v[50:51]
	v_mov_b32_e32 v50, v52
	v_mov_b32_e32 v51, v55
	v_pk_fma_f32 v[60:61], v[50:51], v[48:49], v[6:7]
	v_mov_b32_e32 v7, v54
	v_mov_b32_e32 v54, v53
	v_mov_b32_e32 v58, v57
	v_mov_b32_e32 v6, v52
	v_mov_b32_e32 v48, v56
	v_pk_mul_f32 v[50:51], v[54:55], v[58:59]
	v_or_b32_e32 v8, 4, v44
	v_pk_fma_f32 v[56:57], v[6:7], v[48:49], v[50:51] neg_lo:[0,0,1] neg_hi:[0,0,1]
	v_or_b32_e32 v6, 2, v44
	v_lshl_add_u32 v7, v6, 3, v62
	v_xor_b32_e32 v7, v13, v7
	v_or_b32_e32 v6, v63, v6
	v_lshl_add_u32 v6, v6, 3, 0
	ds_read_b128 v[48:51], v7 offset:16896
	ds_read_b128 v[52:55], v6
	v_cndmask_b32_e64 v7, -v60, v56, vcc
	v_cndmask_b32_e64 v6, -v61, v57, vcc
	v_lshl_add_u32 v37, v8, 3, v62
	v_xor_b32_e32 v37, v13, v37
	s_waitcnt lgkmcnt(1)
	v_mov_b32_e32 v56, v49
	v_mov_b32_e32 v57, v50
	s_waitcnt lgkmcnt(0)
	v_mov_b32_e32 v60, v52
	v_mov_b32_e32 v61, v55
	v_mov_b32_e32 v58, v53
	v_mov_b32_e32 v59, v54
	v_pk_mul_f32 v[56:57], v[56:57], v[60:61]
	v_mov_b32_e32 v60, v48
	v_mov_b32_e32 v61, v51
	v_pk_fma_f32 v[56:57], v[60:61], v[58:59], v[56:57]
	v_mov_b32_e32 v59, v50
	v_mov_b32_e32 v61, v54
	v_mov_b32_e32 v50, v49
	v_mov_b32_e32 v54, v53
	v_or_b32_e32 v8, v63, v8
	v_mov_b32_e32 v58, v48
	v_mov_b32_e32 v60, v52
	v_pk_mul_f32 v[48:49], v[50:51], v[54:55]
	v_lshl_add_u32 v8, v8, 3, 0
	v_pk_fma_f32 v[58:59], v[58:59], v[60:61], v[48:49] neg_lo:[0,0,1] neg_hi:[0,0,1]
	ds_read_b128 v[48:51], v37 offset:16896
	ds_read_b128 v[52:55], v8
	v_cndmask_b32_e64 v37, -v56, v58, vcc
	v_cndmask_b32_e64 v8, -v57, v59, vcc
	v_or_b32_e32 v44, 6, v44
	s_waitcnt lgkmcnt(1)
	v_mov_b32_e32 v56, v49
	v_mov_b32_e32 v57, v50
	s_waitcnt lgkmcnt(0)
	v_mov_b32_e32 v60, v52
	v_mov_b32_e32 v61, v55
	v_mov_b32_e32 v58, v53
	v_mov_b32_e32 v59, v54
	v_pk_mul_f32 v[56:57], v[56:57], v[60:61]
	v_mov_b32_e32 v60, v48
	v_mov_b32_e32 v61, v51
	v_mov_b32_e32 v84, v48
	v_lshl_add_u32 v48, v44, 3, v62
	v_xor_b32_e32 v48, v13, v48
	v_or_b32_e32 v44, v63, v44
	v_pk_fma_f32 v[82:83], v[60:61], v[58:59], v[56:57]
	v_lshl_add_u32 v44, v44, 3, 0
	ds_read_b128 v[56:59], v48 offset:16896
	ds_read_b128 v[60:63], v44
	v_mov_b32_e32 v85, v50
	v_mov_b32_e32 v87, v54
	v_mov_b32_e32 v50, v49
	v_mov_b32_e32 v54, v53
	v_mov_b32_e32 v86, v52
	v_pk_mul_f32 v[48:49], v[50:51], v[54:55]
	s_waitcnt lgkmcnt(0)
	v_pk_mul_f32 v[50:51], v[56:57], v[60:61] op_sel:[1,0] op_sel_hi:[0,1]
	v_pk_fma_f32 v[48:49], v[84:85], v[86:87], v[48:49] neg_lo:[0,0,1] neg_hi:[0,0,1]
	s_nop 0
	v_cndmask_b32_e64 v44, -v83, v49, vcc
	v_add_f32_e32 v49, v50, v51
	v_pk_mul_f32 v[50:51], v[56:57], v[60:61]
	v_cndmask_b32_e64 v48, -v82, v48, vcc
	v_sub_f32_e32 v50, v50, v51
	v_cndmask_b32_e64 v49, -v49, v50, vcc
	v_pk_mul_f32 v[50:51], v[58:59], v[62:63] op_sel:[1,0] op_sel_hi:[0,1]
	v_add_f32_e32 v52, v50, v51
	v_pk_mul_f32 v[50:51], v[58:59], v[62:63]
	s_nop 0
	v_sub_f32_e32 v50, v50, v51
	v_cndmask_b32_e64 v50, -v52, v50, vcc
